# P1 start stagger sleep 16 instead of 24 (mask 3)
# baseline (speedup 1.0000x reference)
; #define REPS(k) for (int rep = 0; rep < ((DUP_PHASE == (k)) ? 2 : 1); ++rep)
; __global__ void __launch_bounds__(NT, 2) fwd(Args args) {
;     ...
;     if (IN(1)) REPS(1) {
;         pg8::Gemm g{AH, WT_IN, MA, NBT, D}; SchedIn S{G, bx, (unsigned*)(ctl + CW_EA), bar.x, bar.st};
;         EpiIn E{CB, UB, QB, KB, VB, MQB, GB, MKB, MVB, out};
;         pg8::gemm_phase<EpiIn, SchedIn, true, true>(lds, g, S, E);
.Lstag:
	s_cmp_eq_u32 s40, 0
	s_cbranch_scc1 .Lstag_done
	s_sleep 16
	s_sub_u32 s40, s40, 1
	s_branch .Lstag
